# gated-norm pass hand-written: all 32 rows' loads of a wave issued before its first wait
# speedup vs baseline: 1.3338x; 1.0036x over previous
.LBB0_678:
	s_or_b64 exec, exec, s[6:7]
	s_lshl_b32 s0, s2, 3
	s_add_i32 s3, s44, s0
	s_cmp_gt_i32 s3, 0xffff
	s_waitcnt lgkmcnt(0)
	s_barrier
	s_cbranch_scc1 .LBB0_689
	v_readlane_b32 s16, v233, 23
	v_readlane_b32 s17, v233, 24
	s_and_b32 s0, s3, 3
	s_lshr_b32 s1, s3, 2
	s_lshl_b32 s1, s1, 5
	s_lshl_b32 s4, s0, 9
	s_lshl_b32 s6, s1, 11
	s_add_u32 s6, s6, s4
	s_add_u32 s6, s6, 0xcc00000
	s_add_u32 s10, s48, s6
	s_addc_u32 s11, s49, 0
	s_lshl_b32 s4, s0, 8
	s_mul_i32 s6, s1, 0x1c00
	s_add_u32 s6, s6, s4
	s_add_u32 s6, s6, 0x3c00c00
	s_add_u32 s12, s48, s6
	s_addc_u32 s13, s49, 0
	s_lshl_b32 s6, s1, 11
	s_add_u32 s6, s6, s4
	s_add_u32 s6, s6, 0xac00000
	s_add_u32 s14, s48, s6
	s_addc_u32 s15, s49, 0
	v_lshrrev_b32_e32 v84, 3, v218
	v_and_b32_e32 v85, 7, v218
	v_lshlrev_b32_e32 v86, 11, v84
	v_lshl_or_b32 v86, v85, 4, v86
	v_mul_u32_u24_e32 v87, 0x1c00, v84
	v_lshl_or_b32 v87, v85, 3, v87
	v_lshlrev_b32_e32 v88, 11, v84
	v_lshl_or_b32 v88, v85, 3, v88
	v_lshlrev_b32_e32 v89, 4, v85
	global_load_dwordx4 v[64:67], v89, s[16:17]
	global_load_dwordx4 v[68:71], v89, s[16:17] offset:128
	global_load_dwordx4 v[72:75], v89, s[16:17] offset:256
	global_load_dwordx4 v[76:79], v89, s[16:17] offset:384
	v_mov_b32_e32 v82, 0x358637bd
	global_load_dwordx4 v[0:3], v86, s[10:11]
	global_load_dwordx4 v[4:7], v86, s[10:11] offset:128
	global_load_dwordx4 v[8:11], v86, s[10:11] offset:256
	global_load_dwordx4 v[12:15], v86, s[10:11] offset:384
	global_load_dwordx2 v[16:17], v87, s[12:13]
	global_load_dwordx2 v[18:19], v87, s[12:13] offset:64
	global_load_dwordx2 v[20:21], v87, s[12:13] offset:128
	global_load_dwordx2 v[22:23], v87, s[12:13] offset:192
	s_add_u32 s10, s10, 0x4000
	s_addc_u32 s11, s11, 0
	s_add_u32 s12, s12, 0xe000
	s_addc_u32 s13, s13, 0
	global_load_dwordx4 v[32:35], v86, s[10:11]
	global_load_dwordx4 v[36:39], v86, s[10:11] offset:128
	global_load_dwordx4 v[40:43], v86, s[10:11] offset:256
	global_load_dwordx4 v[44:47], v86, s[10:11] offset:384
	global_load_dwordx2 v[48:49], v87, s[12:13]
	global_load_dwordx2 v[50:51], v87, s[12:13] offset:64
	global_load_dwordx2 v[52:53], v87, s[12:13] offset:128
	global_load_dwordx2 v[54:55], v87, s[12:13] offset:192
	s_add_u32 s10, s10, 0x4000
	s_addc_u32 s11, s11, 0
	s_add_u32 s12, s12, 0xe000
	s_addc_u32 s13, s13, 0
	global_load_dwordx4 v[172:175], v86, s[10:11]
	global_load_dwordx4 v[176:179], v86, s[10:11] offset:128
	global_load_dwordx4 v[180:183], v86, s[10:11] offset:256
	global_load_dwordx4 v[184:187], v86, s[10:11] offset:384
	global_load_dwordx2 v[152:153], v87, s[12:13]
	global_load_dwordx2 v[154:155], v87, s[12:13] offset:64
	global_load_dwordx2 v[156:157], v87, s[12:13] offset:128
	global_load_dwordx2 v[158:159], v87, s[12:13] offset:192
	s_add_u32 s10, s10, 0x4000
	s_addc_u32 s11, s11, 0
	s_add_u32 s12, s12, 0xe000
	s_addc_u32 s13, s13, 0
	global_load_dwordx4 v[192:195], v86, s[10:11]
	global_load_dwordx4 v[196:199], v86, s[10:11] offset:128
	global_load_dwordx4 v[200:203], v86, s[10:11] offset:256
	global_load_dwordx4 v[204:207], v86, s[10:11] offset:384
	global_load_dwordx2 v[128:129], v87, s[12:13]
	global_load_dwordx2 v[130:131], v87, s[12:13] offset:64
	global_load_dwordx2 v[132:133], v87, s[12:13] offset:128
	global_load_dwordx2 v[134:135], v87, s[12:13] offset:192
	s_add_u32 s10, s10, 0x4000
	s_addc_u32 s11, s11, 0
	s_add_u32 s12, s12, 0xe000
	s_addc_u32 s13, s13, 0
	s_waitcnt vmcnt(24)
	v_mul_f32_e32 v80, v0, v0
	v_fmac_f32_e32 v80, v1, v1
	v_lshlrev_b32_e32 v96, 16, v16
	v_fmac_f32_e32 v80, v2, v2
	v_and_b32_e32 v97, 0xffff0000, v16
	v_fmac_f32_e32 v80, v3, v3
	v_lshlrev_b32_e32 v98, 16, v17
	v_fmac_f32_e32 v80, v4, v4
	v_and_b32_e32 v99, 0xffff0000, v17
	v_fmac_f32_e32 v80, v5, v5
	v_lshlrev_b32_e32 v100, 16, v18
	v_fmac_f32_e32 v80, v6, v6
	v_and_b32_e32 v101, 0xffff0000, v18
	v_fmac_f32_e32 v80, v7, v7
	v_lshlrev_b32_e32 v102, 16, v19
	v_fmac_f32_e32 v80, v8, v8
	v_and_b32_e32 v103, 0xffff0000, v19
	v_fmac_f32_e32 v80, v9, v9
	v_lshlrev_b32_e32 v104, 16, v20
	v_fmac_f32_e32 v80, v10, v10
	v_and_b32_e32 v105, 0xffff0000, v20
	v_fmac_f32_e32 v80, v11, v11
	v_lshlrev_b32_e32 v106, 16, v21
	v_fmac_f32_e32 v80, v12, v12
	v_and_b32_e32 v107, 0xffff0000, v21
	v_fmac_f32_e32 v80, v13, v13
	v_lshlrev_b32_e32 v108, 16, v22
	v_fmac_f32_e32 v80, v14, v14
	v_and_b32_e32 v109, 0xffff0000, v22
	v_fmac_f32_e32 v80, v15, v15
	v_lshlrev_b32_e32 v110, 16, v23
	v_and_b32_e32 v111, 0xffff0000, v23
	v_mul_f32_e32 v112, 0xbfb8aa3b, v96
	v_mul_f32_e32 v113, 0xbfb8aa3b, v97
	v_mul_f32_e32 v114, 0xbfb8aa3b, v98
	v_mul_f32_e32 v115, 0xbfb8aa3b, v99
	v_mul_f32_e32 v116, 0xbfb8aa3b, v100
	v_mul_f32_e32 v117, 0xbfb8aa3b, v101
	v_mul_f32_e32 v118, 0xbfb8aa3b, v102
	v_mul_f32_e32 v119, 0xbfb8aa3b, v103
	v_mul_f32_e32 v120, 0xbfb8aa3b, v104
	v_mul_f32_e32 v121, 0xbfb8aa3b, v105
	v_mul_f32_e32 v122, 0xbfb8aa3b, v106
	v_mul_f32_e32 v123, 0xbfb8aa3b, v107
	v_mul_f32_e32 v124, 0xbfb8aa3b, v108
	v_mul_f32_e32 v125, 0xbfb8aa3b, v109
	v_mul_f32_e32 v126, 0xbfb8aa3b, v110
	v_mul_f32_e32 v127, 0xbfb8aa3b, v111
	v_add_f32_dpp v80, v80, v80 quad_perm:[1,0,3,2] row_mask:0xf bank_mask:0xf bound_ctrl:1
	v_exp_f32_e32 v112, v112
	v_exp_f32_e32 v113, v113
	v_exp_f32_e32 v114, v114
	v_exp_f32_e32 v115, v115
	v_add_f32_dpp v80, v80, v80 quad_perm:[2,3,0,1] row_mask:0xf bank_mask:0xf bound_ctrl:1
	v_exp_f32_e32 v116, v116
	v_exp_f32_e32 v117, v117
	v_exp_f32_e32 v118, v118
	v_exp_f32_e32 v119, v119
	v_add_f32_dpp v80, v80, v80 row_half_mirror row_mask:0xf bank_mask:0xf bound_ctrl:1
	v_exp_f32_e32 v120, v120
	v_exp_f32_e32 v121, v121
	v_exp_f32_e32 v122, v122
	v_exp_f32_e32 v123, v123
	v_exp_f32_e32 v124, v124
	v_exp_f32_e32 v125, v125
	v_exp_f32_e32 v126, v126
	v_exp_f32_e32 v127, v127
	v_fmamk_f32 v81, v80, 0x3c000000, v82
	v_add_f32_e32 v112, 1.0, v112
	v_add_f32_e32 v113, 1.0, v113
	v_add_f32_e32 v114, 1.0, v114
	v_add_f32_e32 v115, 1.0, v115
	v_add_f32_e32 v116, 1.0, v116
	v_add_f32_e32 v117, 1.0, v117
	v_add_f32_e32 v118, 1.0, v118
	v_add_f32_e32 v119, 1.0, v119
	v_add_f32_e32 v120, 1.0, v120
	v_add_f32_e32 v121, 1.0, v121
	v_add_f32_e32 v122, 1.0, v122
	v_add_f32_e32 v123, 1.0, v123
	v_add_f32_e32 v124, 1.0, v124
	v_add_f32_e32 v125, 1.0, v125
	v_add_f32_e32 v126, 1.0, v126
	v_add_f32_e32 v127, 1.0, v127
	v_rsq_f32_e32 v81, v81
	v_rcp_f32_e32 v112, v112
	v_rcp_f32_e32 v113, v113
	v_rcp_f32_e32 v114, v114
	v_rcp_f32_e32 v115, v115
	v_rcp_f32_e32 v116, v116
	v_rcp_f32_e32 v117, v117
	v_rcp_f32_e32 v118, v118
	v_rcp_f32_e32 v119, v119
	v_rcp_f32_e32 v120, v120
	v_rcp_f32_e32 v121, v121
	v_rcp_f32_e32 v122, v122
	v_rcp_f32_e32 v123, v123
	v_rcp_f32_e32 v124, v124
	v_rcp_f32_e32 v125, v125
	v_rcp_f32_e32 v126, v126
	v_rcp_f32_e32 v127, v127
	v_mul_f32_e32 v112, v112, v96
	v_mul_f32_e32 v113, v113, v97
	v_mul_f32_e32 v114, v114, v98
	v_mul_f32_e32 v115, v115, v99
	v_mul_f32_e32 v116, v116, v100
	v_mul_f32_e32 v117, v117, v101
	v_mul_f32_e32 v118, v118, v102
	v_mul_f32_e32 v119, v119, v103
	v_mul_f32_e32 v120, v120, v104
	v_mul_f32_e32 v121, v121, v105
	v_mul_f32_e32 v122, v122, v106
	v_mul_f32_e32 v123, v123, v107
	v_mul_f32_e32 v124, v124, v108
	v_mul_f32_e32 v125, v125, v109
	v_mul_f32_e32 v126, v126, v110
	v_mul_f32_e32 v127, v127, v111
	v_mul_f32_e32 v96, v0, v81
	v_mul_f32_e32 v97, v1, v81
	v_mul_f32_e32 v98, v2, v81
	v_mul_f32_e32 v99, v3, v81
	v_mul_f32_e32 v100, v4, v81
	v_mul_f32_e32 v101, v5, v81
	v_mul_f32_e32 v102, v6, v81
	v_mul_f32_e32 v103, v7, v81
	v_mul_f32_e32 v104, v8, v81
	v_mul_f32_e32 v105, v9, v81
	v_mul_f32_e32 v106, v10, v81
	v_mul_f32_e32 v107, v11, v81
	v_mul_f32_e32 v108, v12, v81
	v_mul_f32_e32 v109, v13, v81
	v_mul_f32_e32 v110, v14, v81
	v_mul_f32_e32 v111, v15, v81
	v_mul_f32_e32 v96, v64, v96
	v_mul_f32_e32 v97, v65, v97
	v_mul_f32_e32 v98, v66, v98
	v_mul_f32_e32 v99, v67, v99
	v_mul_f32_e32 v100, v68, v100
	v_mul_f32_e32 v101, v69, v101
	v_mul_f32_e32 v102, v70, v102
	v_mul_f32_e32 v103, v71, v103
	v_mul_f32_e32 v104, v72, v104
	v_mul_f32_e32 v105, v73, v105
	v_mul_f32_e32 v106, v74, v106
	v_mul_f32_e32 v107, v75, v107
	v_mul_f32_e32 v108, v76, v108
	v_mul_f32_e32 v109, v77, v109
	v_mul_f32_e32 v110, v78, v110
	v_mul_f32_e32 v111, v79, v111
	v_mul_f32_e32 v96, v112, v96
	v_mul_f32_e32 v97, v113, v97
	v_mul_f32_e32 v98, v114, v98
	v_mul_f32_e32 v99, v115, v99
	v_mul_f32_e32 v100, v116, v100
	v_mul_f32_e32 v101, v117, v101
	v_mul_f32_e32 v102, v118, v102
	v_mul_f32_e32 v103, v119, v103
	v_mul_f32_e32 v104, v120, v104
	v_mul_f32_e32 v105, v121, v105
	v_mul_f32_e32 v106, v122, v106
	v_mul_f32_e32 v107, v123, v107
	v_mul_f32_e32 v108, v124, v108
	v_mul_f32_e32 v109, v125, v109
	v_mul_f32_e32 v110, v126, v110
	v_mul_f32_e32 v111, v127, v111
	v_cvt_pk_bf16_f32 v144, v96, v97
	v_cvt_pk_bf16_f32 v145, v98, v99
	v_cvt_pk_bf16_f32 v146, v100, v101
	v_cvt_pk_bf16_f32 v147, v102, v103
	v_cvt_pk_bf16_f32 v148, v104, v105
	v_cvt_pk_bf16_f32 v149, v106, v107
	v_cvt_pk_bf16_f32 v150, v108, v109
	v_cvt_pk_bf16_f32 v151, v110, v111
	global_store_dwordx2 v88, v[144:145], s[14:15]
	global_store_dwordx2 v88, v[146:147], s[14:15] offset:64
	global_store_dwordx2 v88, v[148:149], s[14:15] offset:128
	global_store_dwordx2 v88, v[150:151], s[14:15] offset:192
	s_add_u32 s14, s14, 0x4000
	s_addc_u32 s15, s15, 0
	s_waitcnt vmcnt(20)
	v_mul_f32_e32 v80, v32, v32
	v_fmac_f32_e32 v80, v33, v33
	v_lshlrev_b32_e32 v96, 16, v48
	v_fmac_f32_e32 v80, v34, v34
	v_and_b32_e32 v97, 0xffff0000, v48
	v_fmac_f32_e32 v80, v35, v35
	v_lshlrev_b32_e32 v98, 16, v49
	v_fmac_f32_e32 v80, v36, v36
	v_and_b32_e32 v99, 0xffff0000, v49
	v_fmac_f32_e32 v80, v37, v37
	v_lshlrev_b32_e32 v100, 16, v50
	v_fmac_f32_e32 v80, v38, v38
	v_and_b32_e32 v101, 0xffff0000, v50
	v_fmac_f32_e32 v80, v39, v39
	v_lshlrev_b32_e32 v102, 16, v51
	v_fmac_f32_e32 v80, v40, v40
	v_and_b32_e32 v103, 0xffff0000, v51
	v_fmac_f32_e32 v80, v41, v41
	v_lshlrev_b32_e32 v104, 16, v52
	v_fmac_f32_e32 v80, v42, v42
	v_and_b32_e32 v105, 0xffff0000, v52
	v_fmac_f32_e32 v80, v43, v43
	v_lshlrev_b32_e32 v106, 16, v53
	v_fmac_f32_e32 v80, v44, v44
	v_and_b32_e32 v107, 0xffff0000, v53
	v_fmac_f32_e32 v80, v45, v45
	v_lshlrev_b32_e32 v108, 16, v54
	v_fmac_f32_e32 v80, v46, v46
	v_and_b32_e32 v109, 0xffff0000, v54
	v_fmac_f32_e32 v80, v47, v47
	v_lshlrev_b32_e32 v110, 16, v55
	v_and_b32_e32 v111, 0xffff0000, v55
	v_mul_f32_e32 v112, 0xbfb8aa3b, v96
	v_mul_f32_e32 v113, 0xbfb8aa3b, v97
	v_mul_f32_e32 v114, 0xbfb8aa3b, v98
	v_mul_f32_e32 v115, 0xbfb8aa3b, v99
	v_mul_f32_e32 v116, 0xbfb8aa3b, v100
	v_mul_f32_e32 v117, 0xbfb8aa3b, v101
	v_mul_f32_e32 v118, 0xbfb8aa3b, v102
	v_mul_f32_e32 v119, 0xbfb8aa3b, v103
	v_mul_f32_e32 v120, 0xbfb8aa3b, v104
	v_mul_f32_e32 v121, 0xbfb8aa3b, v105
	v_mul_f32_e32 v122, 0xbfb8aa3b, v106
	v_mul_f32_e32 v123, 0xbfb8aa3b, v107
	v_mul_f32_e32 v124, 0xbfb8aa3b, v108
	v_mul_f32_e32 v125, 0xbfb8aa3b, v109
	v_mul_f32_e32 v126, 0xbfb8aa3b, v110
	v_mul_f32_e32 v127, 0xbfb8aa3b, v111
	v_add_f32_dpp v80, v80, v80 quad_perm:[1,0,3,2] row_mask:0xf bank_mask:0xf bound_ctrl:1
	v_exp_f32_e32 v112, v112
	v_exp_f32_e32 v113, v113
	v_exp_f32_e32 v114, v114
	v_exp_f32_e32 v115, v115
	v_add_f32_dpp v80, v80, v80 quad_perm:[2,3,0,1] row_mask:0xf bank_mask:0xf bound_ctrl:1
	v_exp_f32_e32 v116, v116
	v_exp_f32_e32 v117, v117
	v_exp_f32_e32 v118, v118
	v_exp_f32_e32 v119, v119
	v_add_f32_dpp v80, v80, v80 row_half_mirror row_mask:0xf bank_mask:0xf bound_ctrl:1
	v_exp_f32_e32 v120, v120
	v_exp_f32_e32 v121, v121
	v_exp_f32_e32 v122, v122
	v_exp_f32_e32 v123, v123
	v_exp_f32_e32 v124, v124
	v_exp_f32_e32 v125, v125
	v_exp_f32_e32 v126, v126
	v_exp_f32_e32 v127, v127
	v_fmamk_f32 v81, v80, 0x3c000000, v82
	v_add_f32_e32 v112, 1.0, v112
	v_add_f32_e32 v113, 1.0, v113
	v_add_f32_e32 v114, 1.0, v114
	v_add_f32_e32 v115, 1.0, v115
	v_add_f32_e32 v116, 1.0, v116
	v_add_f32_e32 v117, 1.0, v117
	v_add_f32_e32 v118, 1.0, v118
	v_add_f32_e32 v119, 1.0, v119
	v_add_f32_e32 v120, 1.0, v120
	v_add_f32_e32 v121, 1.0, v121
	v_add_f32_e32 v122, 1.0, v122
	v_add_f32_e32 v123, 1.0, v123
	v_add_f32_e32 v124, 1.0, v124
	v_add_f32_e32 v125, 1.0, v125
	v_add_f32_e32 v126, 1.0, v126
	v_add_f32_e32 v127, 1.0, v127
	v_rsq_f32_e32 v81, v81
	v_rcp_f32_e32 v112, v112
	v_rcp_f32_e32 v113, v113
	v_rcp_f32_e32 v114, v114
	v_rcp_f32_e32 v115, v115
	v_rcp_f32_e32 v116, v116
	v_rcp_f32_e32 v117, v117
	v_rcp_f32_e32 v118, v118
	v_rcp_f32_e32 v119, v119
	v_rcp_f32_e32 v120, v120
	v_rcp_f32_e32 v121, v121
	v_rcp_f32_e32 v122, v122
	v_rcp_f32_e32 v123, v123
	v_rcp_f32_e32 v124, v124
	v_rcp_f32_e32 v125, v125
	v_rcp_f32_e32 v126, v126
	v_rcp_f32_e32 v127, v127
	v_mul_f32_e32 v112, v112, v96
	v_mul_f32_e32 v113, v113, v97
	v_mul_f32_e32 v114, v114, v98
	v_mul_f32_e32 v115, v115, v99
	v_mul_f32_e32 v116, v116, v100
	v_mul_f32_e32 v117, v117, v101
	v_mul_f32_e32 v118, v118, v102
	v_mul_f32_e32 v119, v119, v103
	v_mul_f32_e32 v120, v120, v104
	v_mul_f32_e32 v121, v121, v105
	v_mul_f32_e32 v122, v122, v106
	v_mul_f32_e32 v123, v123, v107
	v_mul_f32_e32 v124, v124, v108
	v_mul_f32_e32 v125, v125, v109
	v_mul_f32_e32 v126, v126, v110
	v_mul_f32_e32 v127, v127, v111
	v_mul_f32_e32 v96, v32, v81
	v_mul_f32_e32 v97, v33, v81
	v_mul_f32_e32 v98, v34, v81
	v_mul_f32_e32 v99, v35, v81
	v_mul_f32_e32 v100, v36, v81
	v_mul_f32_e32 v101, v37, v81
	v_mul_f32_e32 v102, v38, v81
	v_mul_f32_e32 v103, v39, v81
	v_mul_f32_e32 v104, v40, v81
	v_mul_f32_e32 v105, v41, v81
	v_mul_f32_e32 v106, v42, v81
	v_mul_f32_e32 v107, v43, v81
	v_mul_f32_e32 v108, v44, v81
	v_mul_f32_e32 v109, v45, v81
	v_mul_f32_e32 v110, v46, v81
	v_mul_f32_e32 v111, v47, v81
	v_mul_f32_e32 v96, v64, v96
	v_mul_f32_e32 v97, v65, v97
	v_mul_f32_e32 v98, v66, v98
	v_mul_f32_e32 v99, v67, v99
	v_mul_f32_e32 v100, v68, v100
	v_mul_f32_e32 v101, v69, v101
	v_mul_f32_e32 v102, v70, v102
	v_mul_f32_e32 v103, v71, v103
	v_mul_f32_e32 v104, v72, v104
	v_mul_f32_e32 v105, v73, v105
	v_mul_f32_e32 v106, v74, v106
	v_mul_f32_e32 v107, v75, v107
	v_mul_f32_e32 v108, v76, v108
	v_mul_f32_e32 v109, v77, v109
	v_mul_f32_e32 v110, v78, v110
	v_mul_f32_e32 v111, v79, v111
	v_mul_f32_e32 v96, v112, v96
	v_mul_f32_e32 v97, v113, v97
	v_mul_f32_e32 v98, v114, v98
	v_mul_f32_e32 v99, v115, v99
	v_mul_f32_e32 v100, v116, v100
	v_mul_f32_e32 v101, v117, v101
	v_mul_f32_e32 v102, v118, v102
	v_mul_f32_e32 v103, v119, v103
	v_mul_f32_e32 v104, v120, v104
	v_mul_f32_e32 v105, v121, v105
	v_mul_f32_e32 v106, v122, v106
	v_mul_f32_e32 v107, v123, v107
	v_mul_f32_e32 v108, v124, v108
	v_mul_f32_e32 v109, v125, v109
	v_mul_f32_e32 v110, v126, v110
	v_mul_f32_e32 v111, v127, v111
	v_cvt_pk_bf16_f32 v144, v96, v97
	v_cvt_pk_bf16_f32 v145, v98, v99
	v_cvt_pk_bf16_f32 v146, v100, v101
	v_cvt_pk_bf16_f32 v147, v102, v103
	v_cvt_pk_bf16_f32 v148, v104, v105
	v_cvt_pk_bf16_f32 v149, v106, v107
	v_cvt_pk_bf16_f32 v150, v108, v109
	v_cvt_pk_bf16_f32 v151, v110, v111
	global_store_dwordx2 v88, v[144:145], s[14:15]
	global_store_dwordx2 v88, v[146:147], s[14:15] offset:64
	global_store_dwordx2 v88, v[148:149], s[14:15] offset:128
	global_store_dwordx2 v88, v[150:151], s[14:15] offset:192
	s_add_u32 s14, s14, 0x4000
	s_addc_u32 s15, s15, 0
	s_waitcnt vmcnt(16)
	v_mul_f32_e32 v80, v172, v172
	v_fmac_f32_e32 v80, v173, v173
	v_lshlrev_b32_e32 v96, 16, v152
	v_fmac_f32_e32 v80, v174, v174
	v_and_b32_e32 v97, 0xffff0000, v152
	v_fmac_f32_e32 v80, v175, v175
	v_lshlrev_b32_e32 v98, 16, v153
	v_fmac_f32_e32 v80, v176, v176
	v_and_b32_e32 v99, 0xffff0000, v153
	v_fmac_f32_e32 v80, v177, v177
	v_lshlrev_b32_e32 v100, 16, v154
	v_fmac_f32_e32 v80, v178, v178
	v_and_b32_e32 v101, 0xffff0000, v154
	v_fmac_f32_e32 v80, v179, v179
	v_lshlrev_b32_e32 v102, 16, v155
	v_fmac_f32_e32 v80, v180, v180
	v_and_b32_e32 v103, 0xffff0000, v155
	v_fmac_f32_e32 v80, v181, v181
	v_lshlrev_b32_e32 v104, 16, v156
	v_fmac_f32_e32 v80, v182, v182
	v_and_b32_e32 v105, 0xffff0000, v156
	v_fmac_f32_e32 v80, v183, v183
	v_lshlrev_b32_e32 v106, 16, v157
	v_fmac_f32_e32 v80, v184, v184
	v_and_b32_e32 v107, 0xffff0000, v157
	v_fmac_f32_e32 v80, v185, v185
	v_lshlrev_b32_e32 v108, 16, v158
	v_fmac_f32_e32 v80, v186, v186
	v_and_b32_e32 v109, 0xffff0000, v158
	v_fmac_f32_e32 v80, v187, v187
	v_lshlrev_b32_e32 v110, 16, v159
	v_and_b32_e32 v111, 0xffff0000, v159
	v_mul_f32_e32 v112, 0xbfb8aa3b, v96
	v_mul_f32_e32 v113, 0xbfb8aa3b, v97
	v_mul_f32_e32 v114, 0xbfb8aa3b, v98
	v_mul_f32_e32 v115, 0xbfb8aa3b, v99
	v_mul_f32_e32 v116, 0xbfb8aa3b, v100
	v_mul_f32_e32 v117, 0xbfb8aa3b, v101
	v_mul_f32_e32 v118, 0xbfb8aa3b, v102
	v_mul_f32_e32 v119, 0xbfb8aa3b, v103
	v_mul_f32_e32 v120, 0xbfb8aa3b, v104
	v_mul_f32_e32 v121, 0xbfb8aa3b, v105
	v_mul_f32_e32 v122, 0xbfb8aa3b, v106
	v_mul_f32_e32 v123, 0xbfb8aa3b, v107
	v_mul_f32_e32 v124, 0xbfb8aa3b, v108
	v_mul_f32_e32 v125, 0xbfb8aa3b, v109
	v_mul_f32_e32 v126, 0xbfb8aa3b, v110
	v_mul_f32_e32 v127, 0xbfb8aa3b, v111
	v_add_f32_dpp v80, v80, v80 quad_perm:[1,0,3,2] row_mask:0xf bank_mask:0xf bound_ctrl:1
	v_exp_f32_e32 v112, v112
	v_exp_f32_e32 v113, v113
	v_exp_f32_e32 v114, v114
	v_exp_f32_e32 v115, v115
	v_add_f32_dpp v80, v80, v80 quad_perm:[2,3,0,1] row_mask:0xf bank_mask:0xf bound_ctrl:1
	v_exp_f32_e32 v116, v116
	v_exp_f32_e32 v117, v117
	v_exp_f32_e32 v118, v118
	v_exp_f32_e32 v119, v119
	v_add_f32_dpp v80, v80, v80 row_half_mirror row_mask:0xf bank_mask:0xf bound_ctrl:1
	v_exp_f32_e32 v120, v120
	v_exp_f32_e32 v121, v121
	v_exp_f32_e32 v122, v122
	v_exp_f32_e32 v123, v123
	v_exp_f32_e32 v124, v124
	v_exp_f32_e32 v125, v125
	v_exp_f32_e32 v126, v126
	v_exp_f32_e32 v127, v127
	v_fmamk_f32 v81, v80, 0x3c000000, v82
	v_add_f32_e32 v112, 1.0, v112
	v_add_f32_e32 v113, 1.0, v113
	v_add_f32_e32 v114, 1.0, v114
	v_add_f32_e32 v115, 1.0, v115
	v_add_f32_e32 v116, 1.0, v116
	v_add_f32_e32 v117, 1.0, v117
	v_add_f32_e32 v118, 1.0, v118
	v_add_f32_e32 v119, 1.0, v119
	v_add_f32_e32 v120, 1.0, v120
	v_add_f32_e32 v121, 1.0, v121
	v_add_f32_e32 v122, 1.0, v122
	v_add_f32_e32 v123, 1.0, v123
	v_add_f32_e32 v124, 1.0, v124
	v_add_f32_e32 v125, 1.0, v125
	v_add_f32_e32 v126, 1.0, v126
	v_add_f32_e32 v127, 1.0, v127
	v_rsq_f32_e32 v81, v81
	v_rcp_f32_e32 v112, v112
	v_rcp_f32_e32 v113, v113
	v_rcp_f32_e32 v114, v114
	v_rcp_f32_e32 v115, v115
	v_rcp_f32_e32 v116, v116
	v_rcp_f32_e32 v117, v117
	v_rcp_f32_e32 v118, v118
	v_rcp_f32_e32 v119, v119
	v_rcp_f32_e32 v120, v120
	v_rcp_f32_e32 v121, v121
	v_rcp_f32_e32 v122, v122
	v_rcp_f32_e32 v123, v123
	v_rcp_f32_e32 v124, v124
	v_rcp_f32_e32 v125, v125
	v_rcp_f32_e32 v126, v126
	v_rcp_f32_e32 v127, v127
	v_mul_f32_e32 v112, v112, v96
	v_mul_f32_e32 v113, v113, v97
	v_mul_f32_e32 v114, v114, v98
	v_mul_f32_e32 v115, v115, v99
	v_mul_f32_e32 v116, v116, v100
	v_mul_f32_e32 v117, v117, v101
	v_mul_f32_e32 v118, v118, v102
	v_mul_f32_e32 v119, v119, v103
	v_mul_f32_e32 v120, v120, v104
	v_mul_f32_e32 v121, v121, v105
	v_mul_f32_e32 v122, v122, v106
	v_mul_f32_e32 v123, v123, v107
	v_mul_f32_e32 v124, v124, v108
	v_mul_f32_e32 v125, v125, v109
	v_mul_f32_e32 v126, v126, v110
	v_mul_f32_e32 v127, v127, v111
	v_mul_f32_e32 v96, v172, v81
	v_mul_f32_e32 v97, v173, v81
	v_mul_f32_e32 v98, v174, v81
	v_mul_f32_e32 v99, v175, v81
	v_mul_f32_e32 v100, v176, v81
	v_mul_f32_e32 v101, v177, v81
	v_mul_f32_e32 v102, v178, v81
	v_mul_f32_e32 v103, v179, v81
	v_mul_f32_e32 v104, v180, v81
	v_mul_f32_e32 v105, v181, v81
	v_mul_f32_e32 v106, v182, v81
	v_mul_f32_e32 v107, v183, v81
	v_mul_f32_e32 v108, v184, v81
	v_mul_f32_e32 v109, v185, v81
	v_mul_f32_e32 v110, v186, v81
	v_mul_f32_e32 v111, v187, v81
	v_mul_f32_e32 v96, v64, v96
	v_mul_f32_e32 v97, v65, v97
	v_mul_f32_e32 v98, v66, v98
	v_mul_f32_e32 v99, v67, v99
	v_mul_f32_e32 v100, v68, v100
	v_mul_f32_e32 v101, v69, v101
	v_mul_f32_e32 v102, v70, v102
	v_mul_f32_e32 v103, v71, v103
	v_mul_f32_e32 v104, v72, v104
	v_mul_f32_e32 v105, v73, v105
	v_mul_f32_e32 v106, v74, v106
	v_mul_f32_e32 v107, v75, v107
	v_mul_f32_e32 v108, v76, v108
	v_mul_f32_e32 v109, v77, v109
	v_mul_f32_e32 v110, v78, v110
	v_mul_f32_e32 v111, v79, v111
	v_mul_f32_e32 v96, v112, v96
	v_mul_f32_e32 v97, v113, v97
	v_mul_f32_e32 v98, v114, v98
	v_mul_f32_e32 v99, v115, v99
	v_mul_f32_e32 v100, v116, v100
	v_mul_f32_e32 v101, v117, v101
	v_mul_f32_e32 v102, v118, v102
	v_mul_f32_e32 v103, v119, v103
	v_mul_f32_e32 v104, v120, v104
	v_mul_f32_e32 v105, v121, v105
	v_mul_f32_e32 v106, v122, v106
	v_mul_f32_e32 v107, v123, v107
	v_mul_f32_e32 v108, v124, v108
	v_mul_f32_e32 v109, v125, v109
	v_mul_f32_e32 v110, v126, v110
	v_mul_f32_e32 v111, v127, v111
	v_cvt_pk_bf16_f32 v144, v96, v97
	v_cvt_pk_bf16_f32 v145, v98, v99
	v_cvt_pk_bf16_f32 v146, v100, v101
	v_cvt_pk_bf16_f32 v147, v102, v103
	v_cvt_pk_bf16_f32 v148, v104, v105
	v_cvt_pk_bf16_f32 v149, v106, v107
	v_cvt_pk_bf16_f32 v150, v108, v109
	v_cvt_pk_bf16_f32 v151, v110, v111
	global_store_dwordx2 v88, v[144:145], s[14:15]
	global_store_dwordx2 v88, v[146:147], s[14:15] offset:64
	global_store_dwordx2 v88, v[148:149], s[14:15] offset:128
	global_store_dwordx2 v88, v[150:151], s[14:15] offset:192
	s_add_u32 s14, s14, 0x4000
	s_addc_u32 s15, s15, 0
	s_waitcnt vmcnt(12)
	v_mul_f32_e32 v80, v192, v192
	v_fmac_f32_e32 v80, v193, v193
	v_lshlrev_b32_e32 v96, 16, v128
	v_fmac_f32_e32 v80, v194, v194
	v_and_b32_e32 v97, 0xffff0000, v128
	v_fmac_f32_e32 v80, v195, v195
	v_lshlrev_b32_e32 v98, 16, v129
	v_fmac_f32_e32 v80, v196, v196
	v_and_b32_e32 v99, 0xffff0000, v129
	v_fmac_f32_e32 v80, v197, v197
	v_lshlrev_b32_e32 v100, 16, v130
	v_fmac_f32_e32 v80, v198, v198
	v_and_b32_e32 v101, 0xffff0000, v130
	v_fmac_f32_e32 v80, v199, v199
	v_lshlrev_b32_e32 v102, 16, v131
	v_fmac_f32_e32 v80, v200, v200
	v_and_b32_e32 v103, 0xffff0000, v131
	v_fmac_f32_e32 v80, v201, v201
	v_lshlrev_b32_e32 v104, 16, v132
	v_fmac_f32_e32 v80, v202, v202
	v_and_b32_e32 v105, 0xffff0000, v132
	v_fmac_f32_e32 v80, v203, v203
	v_lshlrev_b32_e32 v106, 16, v133
	v_fmac_f32_e32 v80, v204, v204
	v_and_b32_e32 v107, 0xffff0000, v133
	v_fmac_f32_e32 v80, v205, v205
	v_lshlrev_b32_e32 v108, 16, v134
	v_fmac_f32_e32 v80, v206, v206
	v_and_b32_e32 v109, 0xffff0000, v134
	v_fmac_f32_e32 v80, v207, v207
	v_lshlrev_b32_e32 v110, 16, v135
	v_and_b32_e32 v111, 0xffff0000, v135
	v_mul_f32_e32 v112, 0xbfb8aa3b, v96
	v_mul_f32_e32 v113, 0xbfb8aa3b, v97
	v_mul_f32_e32 v114, 0xbfb8aa3b, v98
	v_mul_f32_e32 v115, 0xbfb8aa3b, v99
	v_mul_f32_e32 v116, 0xbfb8aa3b, v100
	v_mul_f32_e32 v117, 0xbfb8aa3b, v101
	v_mul_f32_e32 v118, 0xbfb8aa3b, v102
	v_mul_f32_e32 v119, 0xbfb8aa3b, v103
	v_mul_f32_e32 v120, 0xbfb8aa3b, v104
	v_mul_f32_e32 v121, 0xbfb8aa3b, v105
	v_mul_f32_e32 v122, 0xbfb8aa3b, v106
	v_mul_f32_e32 v123, 0xbfb8aa3b, v107
	v_mul_f32_e32 v124, 0xbfb8aa3b, v108
	v_mul_f32_e32 v125, 0xbfb8aa3b, v109
	v_mul_f32_e32 v126, 0xbfb8aa3b, v110
	v_mul_f32_e32 v127, 0xbfb8aa3b, v111
	v_add_f32_dpp v80, v80, v80 quad_perm:[1,0,3,2] row_mask:0xf bank_mask:0xf bound_ctrl:1
	v_exp_f32_e32 v112, v112
	v_exp_f32_e32 v113, v113
	v_exp_f32_e32 v114, v114
	v_exp_f32_e32 v115, v115
	v_add_f32_dpp v80, v80, v80 quad_perm:[2,3,0,1] row_mask:0xf bank_mask:0xf bound_ctrl:1
	v_exp_f32_e32 v116, v116
	v_exp_f32_e32 v117, v117
	v_exp_f32_e32 v118, v118
	v_exp_f32_e32 v119, v119
	v_add_f32_dpp v80, v80, v80 row_half_mirror row_mask:0xf bank_mask:0xf bound_ctrl:1
	v_exp_f32_e32 v120, v120
	v_exp_f32_e32 v121, v121
	v_exp_f32_e32 v122, v122
	v_exp_f32_e32 v123, v123
	v_exp_f32_e32 v124, v124
	v_exp_f32_e32 v125, v125
	v_exp_f32_e32 v126, v126
	v_exp_f32_e32 v127, v127
	v_fmamk_f32 v81, v80, 0x3c000000, v82
	v_add_f32_e32 v112, 1.0, v112
	v_add_f32_e32 v113, 1.0, v113
	v_add_f32_e32 v114, 1.0, v114
	v_add_f32_e32 v115, 1.0, v115
	v_add_f32_e32 v116, 1.0, v116
	v_add_f32_e32 v117, 1.0, v117
	v_add_f32_e32 v118, 1.0, v118
	v_add_f32_e32 v119, 1.0, v119
	v_add_f32_e32 v120, 1.0, v120
	v_add_f32_e32 v121, 1.0, v121
	v_add_f32_e32 v122, 1.0, v122
	v_add_f32_e32 v123, 1.0, v123
	v_add_f32_e32 v124, 1.0, v124
	v_add_f32_e32 v125, 1.0, v125
	v_add_f32_e32 v126, 1.0, v126
	v_add_f32_e32 v127, 1.0, v127
	v_rsq_f32_e32 v81, v81
	v_rcp_f32_e32 v112, v112
	v_rcp_f32_e32 v113, v113
	v_rcp_f32_e32 v114, v114
	v_rcp_f32_e32 v115, v115
	v_rcp_f32_e32 v116, v116
	v_rcp_f32_e32 v117, v117
	v_rcp_f32_e32 v118, v118
	v_rcp_f32_e32 v119, v119
	v_rcp_f32_e32 v120, v120
	v_rcp_f32_e32 v121, v121
	v_rcp_f32_e32 v122, v122
	v_rcp_f32_e32 v123, v123
	v_rcp_f32_e32 v124, v124
	v_rcp_f32_e32 v125, v125
	v_rcp_f32_e32 v126, v126
	v_rcp_f32_e32 v127, v127
	v_mul_f32_e32 v112, v112, v96
	v_mul_f32_e32 v113, v113, v97
	v_mul_f32_e32 v114, v114, v98
	v_mul_f32_e32 v115, v115, v99
	v_mul_f32_e32 v116, v116, v100
	v_mul_f32_e32 v117, v117, v101
	v_mul_f32_e32 v118, v118, v102
	v_mul_f32_e32 v119, v119, v103
	v_mul_f32_e32 v120, v120, v104
	v_mul_f32_e32 v121, v121, v105
	v_mul_f32_e32 v122, v122, v106
	v_mul_f32_e32 v123, v123, v107
	v_mul_f32_e32 v124, v124, v108
	v_mul_f32_e32 v125, v125, v109
	v_mul_f32_e32 v126, v126, v110
	v_mul_f32_e32 v127, v127, v111
	v_mul_f32_e32 v96, v192, v81
	v_mul_f32_e32 v97, v193, v81
	v_mul_f32_e32 v98, v194, v81
	v_mul_f32_e32 v99, v195, v81
	v_mul_f32_e32 v100, v196, v81
	v_mul_f32_e32 v101, v197, v81
	v_mul_f32_e32 v102, v198, v81
	v_mul_f32_e32 v103, v199, v81
	v_mul_f32_e32 v104, v200, v81
	v_mul_f32_e32 v105, v201, v81
	v_mul_f32_e32 v106, v202, v81
	v_mul_f32_e32 v107, v203, v81
	v_mul_f32_e32 v108, v204, v81
	v_mul_f32_e32 v109, v205, v81
	v_mul_f32_e32 v110, v206, v81
	v_mul_f32_e32 v111, v207, v81
	v_mul_f32_e32 v96, v64, v96
	v_mul_f32_e32 v97, v65, v97
	v_mul_f32_e32 v98, v66, v98
	v_mul_f32_e32 v99, v67, v99
	v_mul_f32_e32 v100, v68, v100
	v_mul_f32_e32 v101, v69, v101
	v_mul_f32_e32 v102, v70, v102
	v_mul_f32_e32 v103, v71, v103
	v_mul_f32_e32 v104, v72, v104
	v_mul_f32_e32 v105, v73, v105
	v_mul_f32_e32 v106, v74, v106
	v_mul_f32_e32 v107, v75, v107
	v_mul_f32_e32 v108, v76, v108
	v_mul_f32_e32 v109, v77, v109
	v_mul_f32_e32 v110, v78, v110
	v_mul_f32_e32 v111, v79, v111
	v_mul_f32_e32 v96, v112, v96
	v_mul_f32_e32 v97, v113, v97
	v_mul_f32_e32 v98, v114, v98
	v_mul_f32_e32 v99, v115, v99
	v_mul_f32_e32 v100, v116, v100
	v_mul_f32_e32 v101, v117, v101
	v_mul_f32_e32 v102, v118, v102
	v_mul_f32_e32 v103, v119, v103
	v_mul_f32_e32 v104, v120, v104
	v_mul_f32_e32 v105, v121, v105
	v_mul_f32_e32 v106, v122, v106
	v_mul_f32_e32 v107, v123, v107
	v_mul_f32_e32 v108, v124, v108
	v_mul_f32_e32 v109, v125, v109
	v_mul_f32_e32 v110, v126, v110
	v_mul_f32_e32 v111, v127, v111
	v_cvt_pk_bf16_f32 v144, v96, v97
	v_cvt_pk_bf16_f32 v145, v98, v99
	v_cvt_pk_bf16_f32 v146, v100, v101
	v_cvt_pk_bf16_f32 v147, v102, v103
	v_cvt_pk_bf16_f32 v148, v104, v105
	v_cvt_pk_bf16_f32 v149, v106, v107
	v_cvt_pk_bf16_f32 v150, v108, v109
	v_cvt_pk_bf16_f32 v151, v110, v111
	global_store_dwordx2 v88, v[144:145], s[14:15]
	global_store_dwordx2 v88, v[146:147], s[14:15] offset:64
	global_store_dwordx2 v88, v[148:149], s[14:15] offset:128
	global_store_dwordx2 v88, v[150:151], s[14:15] offset:192
	s_add_u32 s14, s14, 0x4000
	s_addc_u32 s15, s15, 0
